# v54 + static s_setprio 1 for waves 0-3 kept through all steps after the prologue (no reset at step end)
# speedup vs baseline: 1.0040x; 1.0040x over previous
.LBB0_374:
	v_cmp_gt_u32_e32 vcc, 0x100, v195
	s_cbranch_vccz .Lmy_p2
	s_setprio 1
